# v135 + light prefetch before exchange spin: gpost gains + first xin set only; ladder-2 gains before its spin
# baseline (speedup 1.0000x reference)
;     __device__ __forceinline__ void exchange(const f32x4 (&acc)[2][2][4][2], const Unit& u, int e, int wr, int wc, int fr, int fq) const {
;     ...
;         if (tid < 256 && lid == 0) __hip_atomic_fetch_add(c, 1u, __ATOMIC_RELAXED, __HIP_MEMORY_SCOPE_AGENT);
;         if (wid == 0) { unsigned sp = 0;
;             while ((unsigned)__builtin_amdgcn_readfirstlane((int)__hip_atomic_load(c, __ATOMIC_RELAXED, __HIP_MEMORY_SCOPE_AGENT)) < 16u) { __builtin_amdgcn_s_sleep(2); if (++sp > (1u << 22)) break; }
;             __builtin_amdgcn_fence(__ATOMIC_ACQUIRE, "agent");
;             if (lid == 0) FL[0] = 1u; }
;     __device__ __forceinline__ void operator()(f32x4 (&acc)[2][2][4][2], const Unit& u, int wr, int wc, int fr, int fq) const {
;     ...
;             for (int m = 0; m < 4; ++m) { const int rl = ai * 128 + wr * 64 + m * 16 + fr; const float r1 = S[rl]; const size_t off = (size_t)(u.pm * 256 + rl) * DM + col0;
; #pragma unroll
;                 for (int bj = 0; bj < 2; ++bj) { const f32x4 xa = *(const f32x4*)(xin + off + bj * 128), xb = *(const f32x4*)(xin + off + bj * 128 + 4);
;                     const f32x4 ga = *(const f32x4*)(gpost + col0 + bj * 128), gb = *(const f32x4*)(gpost + col0 + bj * 128 + 4);
.LBB0_89:
	s_or_b64 exec, exec, s[50:51]
	s_lshl_b32 s65, s82, 8
	v_add_u32_e32 v164, s65, v170
	v_lshl_or_b32 v162, s78, 8, v190
	v_ashrrev_i32_e32 v165, 31, v164
	v_ashrrev_i32_e32 v163, 31, v162
	v_lshlrev_b64 v[164:165], 12, v[164:165]
	v_lshl_add_u64 v[164:165], s[34:35], 0, v[164:165]
	v_lshlrev_b64 v[158:159], 2, v[162:163]
	v_lshl_add_u64 v[160:161], v[164:165], 0, v[158:159]
	v_lshl_add_u64 v[154:155], s[52:53], 0, v[158:159]
	global_load_dwordx4 v[218:221], v[154:155], off
	global_load_dwordx4 v[222:225], v[154:155], off offset:16
	global_load_dwordx4 v[226:229], v[154:155], off offset:512
	global_load_dwordx4 v[230:233], v[154:155], off offset:528
	global_load_dwordx4 v[202:205], v[160:161], off offset:16
	global_load_dwordx4 v[206:209], v[160:161], off
	global_load_dwordx4 v[210:213], v[160:161], off offset:528
	global_load_dwordx4 v[214:217], v[160:161], off offset:512
	v_readlane_b32 s68, v253, 15
	v_readlane_b32 s69, v253, 16
	s_andn2_b64 vcc, exec, s[68:69]
	s_nop 0
	v_cndmask_b32_e64 v144, 0, 1, s[68:69]
	v_cmp_ne_u32_e64 s[50:51], 1, v144
	s_cbranch_vccnz .LBB0_101
	s_mov_b32 s65, 0x400001
	s_branch .LBB0_92

; #define LAS __attribute__((address_space(3)))
;     __device__ __forceinline__ void exchange(const f32x4 (&acc)[2][2][4][2], const Unit& u, int e, int wr, int wc, int fr, int fq) const {
;     ...
;         __syncthreads();
;     }
;     __device__ __forceinline__ void operator()(f32x4 (&acc)[2][2][4][2], const Unit& u, int wr, int wc, int fr, int fq) const {
;         const LAS float* S = (const LAS float*)(lds + EN_S);
;         const int col0 = u.pn * 256 + wc * 32 + 8 * fq;
;         exchange(acc, u, 0, wr, wc, fr, fq);
; #pragma unroll
;         for (int ai = 0; ai < 2; ++ai)
; #pragma unroll
;             for (int m = 0; m < 4; ++m) { const int rl = ai * 128 + wr * 64 + m * 16 + fr; const float r1 = S[rl]; const size_t off = (size_t)(u.pm * 256 + rl) * DM + col0;
; #pragma unroll
;                 for (int bj = 0; bj < 2; ++bj) { const f32x4 xa = *(const f32x4*)(xin + off + bj * 128), xb = *(const f32x4*)(xin + off + bj * 128 + 4);
;                     const f32x4 ga = *(const f32x4*)(gpost + col0 + bj * 128), gb = *(const f32x4*)(gpost + col0 + bj * 128 + 4);
;                     const f32x4 v0 = xa + acc[ai][bj][m][0] * r1 * ga, v1 = xb + acc[ai][bj][m][1] * r1 * gb;
;                     *(f32x4*)(xout + off + bj * 128) = v0; *(f32x4*)(xout + off + bj * 128 + 4) = v1; acc[ai][bj][m][0] = v0; acc[ai][bj][m][1] = v1; }
.LBB0_103:
	s_or_b64 exec, exec, s[84:85]
	s_lshl_b32 s54, s82, 8
	v_add_u32_e32 v144, s54, v170
	v_lshl_or_b32 v142, s78, 8, v190
	v_ashrrev_i32_e32 v145, 31, v144
	v_ashrrev_i32_e32 v143, 31, v142
	v_lshlrev_b64 v[146:147], 12, v[144:145]
	v_lshl_add_u64 v[146:147], s[34:35], 0, v[146:147]
	v_lshlrev_b64 v[158:159], 2, v[142:143]
	v_lshl_add_u64 v[160:161], v[146:147], 0, v[158:159]
	v_lshl_add_u64 v[154:155], s[52:53], 0, v[158:159]
	s_waitcnt lgkmcnt(0)
	s_barrier
	s_andn2_b64 vcc, exec, s[62:63]
	ds_read_b32 v154, v182
	v_add_u32_e32 v164, s54, v173
	v_ashrrev_i32_e32 v165, 31, v164
	v_lshlrev_b64 v[164:165], 12, v[164:165]
	v_lshl_add_u64 v[164:165], s[34:35], 0, v[164:165]
	v_lshl_add_u64 v[162:163], v[164:165], 0, v[158:159]
	ds_read_b32 v156, v183
	global_load_dwordx4 v[234:237], v[162:163], off offset:16
	global_load_dwordx4 v[238:241], v[162:163], off
	global_load_dwordx4 v[242:245], v[162:163], off offset:528
	global_load_dwordx4 v[246:249], v[162:163], off offset:512
	s_waitcnt lgkmcnt(1)
	v_pk_mul_f32 v[50:51], v[50:51], v[154:155] op_sel_hi:[1,0]
	v_pk_mul_f32 v[52:53], v[52:53], v[154:155] op_sel_hi:[1,0]
	v_pk_mul_f32 v[54:55], v[54:55], v[154:155] op_sel_hi:[1,0]
	v_pk_mul_f32 v[56:57], v[56:57], v[154:155] op_sel_hi:[1,0]
	v_pk_mul_f32 v[62:63], v[62:63], v[154:155] op_sel_hi:[1,0]
	v_pk_mul_f32 v[64:65], v[64:65], v[154:155] op_sel_hi:[1,0]
	v_pk_mul_f32 v[58:59], v[58:59], v[154:155] op_sel_hi:[1,0]
	v_pk_mul_f32 v[60:61], v[60:61], v[154:155] op_sel_hi:[1,0]
	s_waitcnt vmcnt(4)
	v_pk_fma_f32 v[54:55], v[54:55], v[222:223], v[202:203]
	v_pk_fma_f32 v[56:57], v[56:57], v[224:225], v[204:205]
	v_pk_fma_f32 v[50:51], v[50:51], v[218:219], v[206:207]
	v_pk_fma_f32 v[52:53], v[52:53], v[220:221], v[208:209]
	v_pk_fma_f32 v[58:59], v[58:59], v[230:231], v[210:211]
	v_pk_fma_f32 v[60:61], v[60:61], v[232:233], v[212:213]
	v_pk_fma_f32 v[62:63], v[62:63], v[226:227], v[214:215]
	v_pk_fma_f32 v[64:65], v[64:65], v[228:229], v[216:217]
	global_store_dwordx4 v[160:161], v[50:53], off
	global_store_dwordx4 v[160:161], v[54:57], off offset:16
	global_store_dwordx4 v[160:161], v[62:65], off offset:512
	global_store_dwordx4 v[160:161], v[58:61], off offset:528
	v_add_u32_e32 v164, s54, v174
	v_ashrrev_i32_e32 v165, 31, v164
	v_lshlrev_b64 v[164:165], 12, v[164:165]
	v_lshl_add_u64 v[164:165], s[34:35], 0, v[164:165]
	v_lshl_add_u64 v[160:161], v[164:165], 0, v[158:159]
	ds_read_b32 v154, v184
	global_load_dwordx4 v[202:205], v[160:161], off offset:16
	global_load_dwordx4 v[206:209], v[160:161], off
	global_load_dwordx4 v[210:213], v[160:161], off offset:528
	global_load_dwordx4 v[214:217], v[160:161], off offset:512
	s_waitcnt lgkmcnt(1)
	v_pk_mul_f32 v[74:75], v[74:75], v[156:157] op_sel_hi:[1,0]
	v_pk_mul_f32 v[76:77], v[76:77], v[156:157] op_sel_hi:[1,0]
	v_pk_mul_f32 v[78:79], v[78:79], v[156:157] op_sel_hi:[1,0]
	v_pk_mul_f32 v[80:81], v[80:81], v[156:157] op_sel_hi:[1,0]
	v_pk_mul_f32 v[94:95], v[94:95], v[156:157] op_sel_hi:[1,0]
	v_pk_mul_f32 v[96:97], v[96:97], v[156:157] op_sel_hi:[1,0]
	v_pk_mul_f32 v[90:91], v[90:91], v[156:157] op_sel_hi:[1,0]
	v_pk_mul_f32 v[92:93], v[92:93], v[156:157] op_sel_hi:[1,0]
	s_waitcnt vmcnt(8)
	v_pk_fma_f32 v[78:79], v[78:79], v[222:223], v[234:235]
	v_pk_fma_f32 v[80:81], v[80:81], v[224:225], v[236:237]
	v_pk_fma_f32 v[74:75], v[74:75], v[218:219], v[238:239]
	v_pk_fma_f32 v[76:77], v[76:77], v[220:221], v[240:241]
	v_pk_fma_f32 v[90:91], v[90:91], v[230:231], v[242:243]
	v_pk_fma_f32 v[92:93], v[92:93], v[232:233], v[244:245]
	v_pk_fma_f32 v[94:95], v[94:95], v[226:227], v[246:247]
	v_pk_fma_f32 v[96:97], v[96:97], v[228:229], v[248:249]
	global_store_dwordx4 v[162:163], v[74:77], off
	global_store_dwordx4 v[162:163], v[78:81], off offset:16
	global_store_dwordx4 v[162:163], v[94:97], off offset:512
	global_store_dwordx4 v[162:163], v[90:93], off offset:528
	v_add_u32_e32 v164, s54, v175
	v_ashrrev_i32_e32 v165, 31, v164
	v_lshlrev_b64 v[164:165], 12, v[164:165]
	v_lshl_add_u64 v[164:165], s[34:35], 0, v[164:165]
	v_lshl_add_u64 v[162:163], v[164:165], 0, v[158:159]
	ds_read_b32 v156, v185
	global_load_dwordx4 v[234:237], v[162:163], off offset:16
	global_load_dwordx4 v[238:241], v[162:163], off
	global_load_dwordx4 v[242:245], v[162:163], off offset:528
	global_load_dwordx4 v[246:249], v[162:163], off offset:512
	s_waitcnt lgkmcnt(1)
	v_pk_mul_f32 v[98:99], v[98:99], v[154:155] op_sel_hi:[1,0]
	v_pk_mul_f32 v[100:101], v[100:101], v[154:155] op_sel_hi:[1,0]
	v_pk_mul_f32 v[102:103], v[102:103], v[154:155] op_sel_hi:[1,0]
	v_pk_mul_f32 v[104:105], v[104:105], v[154:155] op_sel_hi:[1,0]
	v_pk_mul_f32 v[118:119], v[118:119], v[154:155] op_sel_hi:[1,0]
	v_pk_mul_f32 v[120:121], v[120:121], v[154:155] op_sel_hi:[1,0]
	v_pk_mul_f32 v[114:115], v[114:115], v[154:155] op_sel_hi:[1,0]
	v_pk_mul_f32 v[116:117], v[116:117], v[154:155] op_sel_hi:[1,0]
	s_waitcnt vmcnt(8)
	v_pk_fma_f32 v[102:103], v[102:103], v[222:223], v[202:203]
	v_pk_fma_f32 v[104:105], v[104:105], v[224:225], v[204:205]
	v_pk_fma_f32 v[98:99], v[98:99], v[218:219], v[206:207]
	v_pk_fma_f32 v[100:101], v[100:101], v[220:221], v[208:209]
	v_pk_fma_f32 v[114:115], v[114:115], v[230:231], v[210:211]
	v_pk_fma_f32 v[116:117], v[116:117], v[232:233], v[212:213]
	v_pk_fma_f32 v[118:119], v[118:119], v[226:227], v[214:215]
	v_pk_fma_f32 v[120:121], v[120:121], v[228:229], v[216:217]
	global_store_dwordx4 v[160:161], v[98:101], off
	global_store_dwordx4 v[160:161], v[102:105], off offset:16
	global_store_dwordx4 v[160:161], v[118:121], off offset:512
	global_store_dwordx4 v[160:161], v[114:117], off offset:528
	v_add_u32_e32 v164, s54, v176
	v_ashrrev_i32_e32 v165, 31, v164
	v_lshlrev_b64 v[164:165], 12, v[164:165]
	v_lshl_add_u64 v[164:165], s[34:35], 0, v[164:165]
	v_lshl_add_u64 v[160:161], v[164:165], 0, v[158:159]
	ds_read_b32 v154, v186
	global_load_dwordx4 v[202:205], v[160:161], off offset:16
	global_load_dwordx4 v[206:209], v[160:161], off
	global_load_dwordx4 v[210:213], v[160:161], off offset:528
	global_load_dwordx4 v[214:217], v[160:161], off offset:512
	s_waitcnt lgkmcnt(1)
;     __device__ __forceinline__ void operator()(f32x4 (&acc)[2][2][4][2], const Unit& u, int wr, int wc, int fr, int fq) const {
;     ...
;             for (int m = 0; m < 4; ++m) { const int rl = ai * 128 + wr * 64 + m * 16 + fr; const float r1 = S[rl]; const size_t off = (size_t)(u.pm * 256 + rl) * DM + col0;
; #pragma unroll
;                 for (int bj = 0; bj < 2; ++bj) { const f32x4 xa = *(const f32x4*)(xin + off + bj * 128), xb = *(const f32x4*)(xin + off + bj * 128 + 4);
;                     const f32x4 ga = *(const f32x4*)(gpost + col0 + bj * 128), gb = *(const f32x4*)(gpost + col0 + bj * 128 + 4);
;                     const f32x4 v0 = xa + acc[ai][bj][m][0] * r1 * ga, v1 = xb + acc[ai][bj][m][1] * r1 * gb;
;                     *(f32x4*)(xout + off + bj * 128) = v0; *(f32x4*)(xout + off + bj * 128 + 4) = v1; acc[ai][bj][m][0] = v0; acc[ai][bj][m][1] = v1; }
	v_pk_mul_f32 v[126:127], v[126:127], v[156:157] op_sel_hi:[1,0]
	v_pk_mul_f32 v[128:129], v[128:129], v[156:157] op_sel_hi:[1,0]
	v_pk_mul_f32 v[122:123], v[122:123], v[156:157] op_sel_hi:[1,0]
	v_pk_mul_f32 v[124:125], v[124:125], v[156:157] op_sel_hi:[1,0]
	v_pk_mul_f32 v[110:111], v[110:111], v[156:157] op_sel_hi:[1,0]
	v_pk_mul_f32 v[112:113], v[112:113], v[156:157] op_sel_hi:[1,0]
	v_pk_mul_f32 v[106:107], v[106:107], v[156:157] op_sel_hi:[1,0]
	v_pk_mul_f32 v[108:109], v[108:109], v[156:157] op_sel_hi:[1,0]
	s_waitcnt vmcnt(8)
	v_pk_fma_f32 v[122:123], v[122:123], v[222:223], v[234:235]
	v_pk_fma_f32 v[124:125], v[124:125], v[224:225], v[236:237]
	v_pk_fma_f32 v[126:127], v[126:127], v[218:219], v[238:239]
	v_pk_fma_f32 v[128:129], v[128:129], v[220:221], v[240:241]
	v_pk_fma_f32 v[106:107], v[106:107], v[230:231], v[242:243]
	v_pk_fma_f32 v[108:109], v[108:109], v[232:233], v[244:245]
	v_pk_fma_f32 v[110:111], v[110:111], v[226:227], v[246:247]
	v_pk_fma_f32 v[112:113], v[112:113], v[228:229], v[248:249]
	global_store_dwordx4 v[162:163], v[126:129], off
	global_store_dwordx4 v[162:163], v[122:125], off offset:16
	global_store_dwordx4 v[162:163], v[110:113], off offset:512
	global_store_dwordx4 v[162:163], v[106:109], off offset:528
	v_add_u32_e32 v164, s54, v177
	v_ashrrev_i32_e32 v165, 31, v164
	v_lshlrev_b64 v[164:165], 12, v[164:165]
	v_lshl_add_u64 v[164:165], s[34:35], 0, v[164:165]
	v_lshl_add_u64 v[162:163], v[164:165], 0, v[158:159]
	ds_read_b32 v156, v187
	global_load_dwordx4 v[234:237], v[162:163], off offset:16
	global_load_dwordx4 v[238:241], v[162:163], off
	global_load_dwordx4 v[242:245], v[162:163], off offset:528
	global_load_dwordx4 v[246:249], v[162:163], off offset:512
	s_waitcnt lgkmcnt(1)
	v_pk_mul_f32 v[86:87], v[86:87], v[154:155] op_sel_hi:[1,0]
	v_pk_mul_f32 v[88:89], v[88:89], v[154:155] op_sel_hi:[1,0]
	v_pk_mul_f32 v[82:83], v[82:83], v[154:155] op_sel_hi:[1,0]
	v_pk_mul_f32 v[84:85], v[84:85], v[154:155] op_sel_hi:[1,0]
	v_pk_mul_f32 v[70:71], v[70:71], v[154:155] op_sel_hi:[1,0]
	v_pk_mul_f32 v[72:73], v[72:73], v[154:155] op_sel_hi:[1,0]
	v_pk_mul_f32 v[66:67], v[66:67], v[154:155] op_sel_hi:[1,0]
	v_pk_mul_f32 v[68:69], v[68:69], v[154:155] op_sel_hi:[1,0]
	s_waitcnt vmcnt(8)
	v_pk_fma_f32 v[82:83], v[82:83], v[222:223], v[202:203]
	v_pk_fma_f32 v[84:85], v[84:85], v[224:225], v[204:205]
	v_pk_fma_f32 v[86:87], v[86:87], v[218:219], v[206:207]
	v_pk_fma_f32 v[88:89], v[88:89], v[220:221], v[208:209]
	v_pk_fma_f32 v[66:67], v[66:67], v[230:231], v[210:211]
	v_pk_fma_f32 v[68:69], v[68:69], v[232:233], v[212:213]
	v_pk_fma_f32 v[70:71], v[70:71], v[226:227], v[214:215]
	v_pk_fma_f32 v[72:73], v[72:73], v[228:229], v[216:217]
	global_store_dwordx4 v[160:161], v[86:89], off
	global_store_dwordx4 v[160:161], v[82:85], off offset:16
	global_store_dwordx4 v[160:161], v[70:73], off offset:512
	global_store_dwordx4 v[160:161], v[66:69], off offset:528
	v_add_u32_e32 v164, s54, v178
	v_ashrrev_i32_e32 v165, 31, v164
	v_lshlrev_b64 v[164:165], 12, v[164:165]
	v_lshl_add_u64 v[164:165], s[34:35], 0, v[164:165]
	v_lshl_add_u64 v[160:161], v[164:165], 0, v[158:159]
	ds_read_b32 v154, v188
	global_load_dwordx4 v[202:205], v[160:161], off offset:16
	global_load_dwordx4 v[206:209], v[160:161], off
	global_load_dwordx4 v[210:213], v[160:161], off offset:528
	global_load_dwordx4 v[214:217], v[160:161], off offset:512
	s_waitcnt lgkmcnt(1)
	v_pk_mul_f32 v[46:47], v[46:47], v[156:157] op_sel_hi:[1,0]
	v_pk_mul_f32 v[48:49], v[48:49], v[156:157] op_sel_hi:[1,0]
	v_pk_mul_f32 v[42:43], v[42:43], v[156:157] op_sel_hi:[1,0]
	v_pk_mul_f32 v[44:45], v[44:45], v[156:157] op_sel_hi:[1,0]
	v_pk_mul_f32 v[38:39], v[38:39], v[156:157] op_sel_hi:[1,0]
	v_pk_mul_f32 v[40:41], v[40:41], v[156:157] op_sel_hi:[1,0]
	v_pk_mul_f32 v[34:35], v[34:35], v[156:157] op_sel_hi:[1,0]
	v_pk_mul_f32 v[36:37], v[36:37], v[156:157] op_sel_hi:[1,0]
	s_waitcnt vmcnt(8)
	v_pk_fma_f32 v[42:43], v[42:43], v[222:223], v[234:235]
	v_pk_fma_f32 v[44:45], v[44:45], v[224:225], v[236:237]
	v_pk_fma_f32 v[46:47], v[46:47], v[218:219], v[238:239]
	v_pk_fma_f32 v[48:49], v[48:49], v[220:221], v[240:241]
	v_pk_fma_f32 v[34:35], v[34:35], v[230:231], v[242:243]
	v_pk_fma_f32 v[36:37], v[36:37], v[232:233], v[244:245]
	v_pk_fma_f32 v[38:39], v[38:39], v[226:227], v[246:247]
	v_pk_fma_f32 v[40:41], v[40:41], v[228:229], v[248:249]
	global_store_dwordx4 v[162:163], v[46:49], off
	global_store_dwordx4 v[162:163], v[42:45], off offset:16
	global_store_dwordx4 v[162:163], v[38:41], off offset:512
	global_store_dwordx4 v[162:163], v[34:37], off offset:528
	v_add_u32_e32 v164, s54, v179
	v_ashrrev_i32_e32 v165, 31, v164
	v_lshlrev_b64 v[164:165], 12, v[164:165]
	v_lshl_add_u64 v[164:165], s[34:35], 0, v[164:165]
	v_lshl_add_u64 v[162:163], v[164:165], 0, v[158:159]
	ds_read_b32 v156, v189
	global_load_dwordx4 v[234:237], v[162:163], off offset:16
	global_load_dwordx4 v[238:241], v[162:163], off
	global_load_dwordx4 v[242:245], v[162:163], off offset:528
	global_load_dwordx4 v[246:249], v[162:163], off offset:512
	s_waitcnt lgkmcnt(1)
	v_pk_mul_f32 v[30:31], v[30:31], v[154:155] op_sel_hi:[1,0]
	v_pk_mul_f32 v[32:33], v[32:33], v[154:155] op_sel_hi:[1,0]
	v_pk_mul_f32 v[26:27], v[26:27], v[154:155] op_sel_hi:[1,0]
	v_pk_mul_f32 v[28:29], v[28:29], v[154:155] op_sel_hi:[1,0]
	v_pk_mul_f32 v[22:23], v[22:23], v[154:155] op_sel_hi:[1,0]
	v_pk_mul_f32 v[24:25], v[24:25], v[154:155] op_sel_hi:[1,0]
	v_pk_mul_f32 v[18:19], v[18:19], v[154:155] op_sel_hi:[1,0]
	v_pk_mul_f32 v[20:21], v[20:21], v[154:155] op_sel_hi:[1,0]
	s_waitcnt vmcnt(8)
; __device__ __forceinline__ float swap_add(float v) { auto rr = __builtin_amdgcn_permlane32_swap(__float_as_uint(v), __float_as_uint(v), false, false); return __uint_as_float(rr[0]) + __uint_as_float(rr[1]); }
;     __device__ __forceinline__ void exchange(const f32x4 (&acc)[2][2][4][2], const Unit& u, int e, int wr, int wc, int fr, int fq) const {
;     ...
;         for (int ai = 0; ai < 2; ++ai)
; #pragma unroll
;             for (int m = 0; m < 4; ++m) { float q = 0.f;
; #pragma unroll
;                 for (int bj = 0; bj < 2; ++bj)
; #pragma unroll
;                     for (int n = 0; n < 2; ++n) { const f32x4 v = acc[ai][bj][m][n]; q += (v[0] * v[0] + v[1] * v[1]) + (v[2] * v[2] + v[3] * v[3]); }
;                 q += __int_as_float(__builtin_amdgcn_ds_bpermute((lid ^ 16) << 2, __float_as_int(q))); q = swap_add(q);
;                 if (fq == 0) P[(ai * 128 + wr * 64 + m * 16 + fr) * 4 + wc] = q; }
;     __device__ __forceinline__ void operator()(f32x4 (&acc)[2][2][4][2], const Unit& u, int wr, int wc, int fr, int fq) const {
;     ...
;                 for (int bj = 0; bj < 2; ++bj) { const f32x4 xa = *(const f32x4*)(xin + off + bj * 128), xb = *(const f32x4*)(xin + off + bj * 128 + 4);
;                     const f32x4 ga = *(const f32x4*)(gpost + col0 + bj * 128), gb = *(const f32x4*)(gpost + col0 + bj * 128 + 4);
;                     const f32x4 v0 = xa + acc[ai][bj][m][0] * r1 * ga, v1 = xb + acc[ai][bj][m][1] * r1 * gb;
;                     *(f32x4*)(xout + off + bj * 128) = v0; *(f32x4*)(xout + off + bj * 128 + 4) = v1; acc[ai][bj][m][0] = v0; acc[ai][bj][m][1] = v1; }
;                 asm volatile("" ::: "memory"); }
;         if (gnext) {
;             exchange(acc, u, 1, wr, wc, fr, fq);
	v_pk_fma_f32 v[26:27], v[26:27], v[222:223], v[202:203]
	v_pk_fma_f32 v[28:29], v[28:29], v[224:225], v[204:205]
	v_pk_fma_f32 v[30:31], v[30:31], v[218:219], v[206:207]
	v_pk_fma_f32 v[32:33], v[32:33], v[220:221], v[208:209]
	v_pk_fma_f32 v[18:19], v[18:19], v[230:231], v[210:211]
	v_pk_fma_f32 v[20:21], v[20:21], v[232:233], v[212:213]
	v_pk_fma_f32 v[22:23], v[22:23], v[226:227], v[214:215]
	v_pk_fma_f32 v[24:25], v[24:25], v[228:229], v[216:217]
	global_store_dwordx4 v[160:161], v[30:33], off
	global_store_dwordx4 v[160:161], v[26:29], off offset:16
	global_store_dwordx4 v[160:161], v[22:25], off offset:512
	global_store_dwordx4 v[160:161], v[18:21], off offset:528
	s_waitcnt lgkmcnt(0)
	v_pk_mul_f32 v[14:15], v[14:15], v[156:157] op_sel_hi:[1,0]
	v_pk_mul_f32 v[16:17], v[16:17], v[156:157] op_sel_hi:[1,0]
	v_pk_mul_f32 v[10:11], v[10:11], v[156:157] op_sel_hi:[1,0]
	v_pk_mul_f32 v[12:13], v[12:13], v[156:157] op_sel_hi:[1,0]
	v_pk_mul_f32 v[6:7], v[6:7], v[156:157] op_sel_hi:[1,0]
	v_pk_mul_f32 v[8:9], v[8:9], v[156:157] op_sel_hi:[1,0]
	v_pk_mul_f32 v[2:3], v[2:3], v[156:157] op_sel_hi:[1,0]
	v_pk_mul_f32 v[4:5], v[4:5], v[156:157] op_sel_hi:[1,0]
	s_waitcnt vmcnt(4)
	v_pk_fma_f32 v[10:11], v[10:11], v[222:223], v[234:235]
	v_pk_fma_f32 v[12:13], v[12:13], v[224:225], v[236:237]
	v_pk_fma_f32 v[14:15], v[14:15], v[218:219], v[238:239]
	v_pk_fma_f32 v[16:17], v[16:17], v[220:221], v[240:241]
	v_pk_fma_f32 v[2:3], v[2:3], v[230:231], v[242:243]
	v_pk_fma_f32 v[4:5], v[4:5], v[232:233], v[244:245]
	v_pk_fma_f32 v[6:7], v[6:7], v[226:227], v[246:247]
	v_pk_fma_f32 v[8:9], v[8:9], v[228:229], v[248:249]
	global_store_dwordx4 v[162:163], v[14:17], off
	global_store_dwordx4 v[162:163], v[10:13], off offset:16
	global_store_dwordx4 v[162:163], v[6:9], off offset:512
	global_store_dwordx4 v[162:163], v[2:5], off offset:528
	v_add_u32_e32 v146, s54, v173
	v_ashrrev_i32_e32 v147, 31, v146
	v_add_u32_e32 v148, s54, v174
	v_ashrrev_i32_e32 v149, 31, v148
	v_add_u32_e32 v150, s54, v175
	v_ashrrev_i32_e32 v151, 31, v150
	v_add_u32_e32 v152, s54, v176
	v_ashrrev_i32_e32 v153, 31, v152
	v_add_u32_e32 v156, s54, v177
	v_ashrrev_i32_e32 v157, 31, v156
	v_add_u32_e32 v166, s54, v178
	v_ashrrev_i32_e32 v167, 31, v166
	v_add_u32_e32 v168, s54, v179
	v_ashrrev_i32_e32 v169, 31, v168
	s_cbranch_vccnz .LBB0_140
	v_mul_f32_e32 v154, v51, v51
	v_mul_f32_e32 v155, v53, v53
	v_fmac_f32_e32 v154, v50, v50
	v_fmac_f32_e32 v155, v52, v52
	v_add_f32_e32 v154, v154, v155
	v_mul_f32_e32 v155, v55, v55
	v_mul_f32_e32 v158, v57, v57
	v_fmac_f32_e32 v155, v54, v54
	v_fmac_f32_e32 v158, v56, v56
	v_add_f32_e32 v155, v155, v158
	v_add_f32_e32 v154, v154, v155
	v_mul_f32_e32 v155, v63, v63
	v_mul_f32_e32 v158, v65, v65
	v_fmac_f32_e32 v155, v62, v62
	v_fmac_f32_e32 v158, v64, v64
	v_add_f32_e32 v155, v155, v158
	v_add_f32_e32 v154, v154, v155
	v_mul_f32_e32 v155, v59, v59
	v_mul_f32_e32 v158, v61, v61
	v_fmac_f32_e32 v155, v58, v58
	v_fmac_f32_e32 v158, v60, v60
	v_add_f32_e32 v155, v155, v158
	v_add_f32_e32 v154, v154, v155
	ds_bpermute_b32 v155, v172, v154
	s_waitcnt lgkmcnt(0)
	v_add_f32_e32 v154, v154, v155
	v_mov_b32_e32 v155, v154
	s_nop 1
	v_permlane32_swap_b32_e32 v154, v155
	s_and_saveexec_b64 s[54:55], s[42:43]
	v_add_f32_e32 v154, v154, v155
	ds_write_b32 v201, v154
	s_or_b64 exec, exec, s[54:55]
	v_mul_f32_e32 v154, v75, v75
	v_mul_f32_e32 v155, v77, v77
	v_fmac_f32_e32 v154, v74, v74
	v_fmac_f32_e32 v155, v76, v76
	v_add_f32_e32 v154, v154, v155
	v_mul_f32_e32 v155, v79, v79
	v_mul_f32_e32 v158, v81, v81
	v_fmac_f32_e32 v155, v78, v78
	v_fmac_f32_e32 v158, v80, v80
	v_add_f32_e32 v155, v155, v158
	v_add_f32_e32 v154, v154, v155
	v_mul_f32_e32 v155, v95, v95
	v_mul_f32_e32 v158, v97, v97
	v_fmac_f32_e32 v155, v94, v94
	v_fmac_f32_e32 v158, v96, v96
	v_add_f32_e32 v155, v155, v158
	v_add_f32_e32 v154, v154, v155
	v_mul_f32_e32 v155, v91, v91
	v_mul_f32_e32 v158, v93, v93
	v_fmac_f32_e32 v155, v90, v90
	v_fmac_f32_e32 v158, v92, v92
	v_add_f32_e32 v155, v155, v158
	v_add_f32_e32 v154, v154, v155
	ds_bpermute_b32 v155, v172, v154
	s_waitcnt lgkmcnt(0)
	v_add_f32_e32 v154, v154, v155
	v_mov_b32_e32 v155, v154
	s_nop 1
	v_permlane32_swap_b32_e32 v154, v155
	s_and_saveexec_b64 s[54:55], s[42:43]
	v_add_f32_e32 v154, v154, v155
	ds_write_b32 v201, v154 offset:256
	s_or_b64 exec, exec, s[54:55]
	v_mul_f32_e32 v154, v99, v99
	v_mul_f32_e32 v155, v101, v101
	v_fmac_f32_e32 v154, v98, v98
	v_fmac_f32_e32 v155, v100, v100
	v_add_f32_e32 v154, v154, v155
	v_mul_f32_e32 v155, v103, v103
	v_mul_f32_e32 v158, v105, v105
	v_fmac_f32_e32 v155, v102, v102
	v_fmac_f32_e32 v158, v104, v104
	v_add_f32_e32 v155, v155, v158
	v_add_f32_e32 v154, v154, v155
	v_mul_f32_e32 v155, v119, v119
	v_mul_f32_e32 v158, v121, v121
	v_fmac_f32_e32 v155, v118, v118
	v_fmac_f32_e32 v158, v120, v120
	v_add_f32_e32 v155, v155, v158
	v_add_f32_e32 v154, v154, v155
	v_mul_f32_e32 v155, v115, v115
	v_mul_f32_e32 v158, v117, v117
	v_fmac_f32_e32 v155, v114, v114
	v_fmac_f32_e32 v158, v116, v116
	v_add_f32_e32 v155, v155, v158
	v_add_f32_e32 v154, v154, v155
	ds_bpermute_b32 v155, v172, v154
	s_waitcnt lgkmcnt(0)
; __device__ __forceinline__ float swap_add(float v) { auto rr = __builtin_amdgcn_permlane32_swap(__float_as_uint(v), __float_as_uint(v), false, false); return __uint_as_float(rr[0]) + __uint_as_float(rr[1]); }
;     __device__ __forceinline__ void exchange(const f32x4 (&acc)[2][2][4][2], const Unit& u, int e, int wr, int wc, int fr, int fq) const {
;     ...
;         for (int ai = 0; ai < 2; ++ai)
; #pragma unroll
;             for (int m = 0; m < 4; ++m) { float q = 0.f;
; #pragma unroll
;                 for (int bj = 0; bj < 2; ++bj)
; #pragma unroll
;                     for (int n = 0; n < 2; ++n) { const f32x4 v = acc[ai][bj][m][n]; q += (v[0] * v[0] + v[1] * v[1]) + (v[2] * v[2] + v[3] * v[3]); }
;                 q += __int_as_float(__builtin_amdgcn_ds_bpermute((lid ^ 16) << 2, __float_as_int(q))); q = swap_add(q);
;                 if (fq == 0) P[(ai * 128 + wr * 64 + m * 16 + fr) * 4 + wc] = q; }
;         __syncthreads();
;         float* xb = xbuf + (size_t)e * T * 4 + (size_t)u.pm * 256 * 4; unsigned* c = cnt + (e * 64 + u.pm) * 64;
;         if (tid < 256) { const float tot = (P[tid * 4] + P[tid * 4 + 1]) + (P[tid * 4 + 2] + P[tid * 4 + 3]);
;             __hip_atomic_store(xb + tid * 4 + u.pn, tot, __ATOMIC_RELAXED, __HIP_MEMORY_SCOPE_AGENT); }
	v_add_f32_e32 v154, v154, v155
	v_mov_b32_e32 v155, v154
	s_nop 1
	v_permlane32_swap_b32_e32 v154, v155
	s_and_saveexec_b64 s[54:55], s[42:43]
	v_add_f32_e32 v154, v154, v155
	ds_write_b32 v201, v154 offset:512
	s_or_b64 exec, exec, s[54:55]
	v_mul_f32_e32 v154, v127, v127
	v_mul_f32_e32 v155, v129, v129
	v_fmac_f32_e32 v154, v126, v126
	v_fmac_f32_e32 v155, v128, v128
	v_add_f32_e32 v154, v154, v155
	v_mul_f32_e32 v155, v123, v123
	v_mul_f32_e32 v158, v125, v125
	v_fmac_f32_e32 v155, v122, v122
	v_fmac_f32_e32 v158, v124, v124
	v_add_f32_e32 v155, v155, v158
	v_add_f32_e32 v154, v154, v155
	v_mul_f32_e32 v155, v111, v111
	v_mul_f32_e32 v158, v113, v113
	v_fmac_f32_e32 v155, v110, v110
	v_fmac_f32_e32 v158, v112, v112
	v_add_f32_e32 v155, v155, v158
	v_add_f32_e32 v154, v154, v155
	v_mul_f32_e32 v155, v107, v107
	v_mul_f32_e32 v158, v109, v109
	v_fmac_f32_e32 v155, v106, v106
	v_fmac_f32_e32 v158, v108, v108
	v_add_f32_e32 v155, v155, v158
	v_add_f32_e32 v154, v154, v155
	ds_bpermute_b32 v155, v172, v154
	s_waitcnt lgkmcnt(0)
	v_add_f32_e32 v154, v154, v155
	v_mov_b32_e32 v155, v154
	s_nop 1
	v_permlane32_swap_b32_e32 v154, v155
	s_and_saveexec_b64 s[54:55], s[42:43]
	v_add_f32_e32 v154, v154, v155
	ds_write_b32 v201, v154 offset:768
	s_or_b64 exec, exec, s[54:55]
	v_mul_f32_e32 v154, v87, v87
	v_mul_f32_e32 v155, v89, v89
	v_fmac_f32_e32 v154, v86, v86
	v_fmac_f32_e32 v155, v88, v88
	v_add_f32_e32 v154, v154, v155
	v_mul_f32_e32 v155, v83, v83
	v_mul_f32_e32 v158, v85, v85
	v_fmac_f32_e32 v155, v82, v82
	v_fmac_f32_e32 v158, v84, v84
	v_add_f32_e32 v155, v155, v158
	v_add_f32_e32 v154, v154, v155
	v_mul_f32_e32 v155, v71, v71
	v_mul_f32_e32 v158, v73, v73
	v_fmac_f32_e32 v155, v70, v70
	v_fmac_f32_e32 v158, v72, v72
	v_add_f32_e32 v155, v155, v158
	v_add_f32_e32 v154, v154, v155
	v_mul_f32_e32 v155, v67, v67
	v_mul_f32_e32 v158, v69, v69
	v_fmac_f32_e32 v155, v66, v66
	v_fmac_f32_e32 v158, v68, v68
	v_add_f32_e32 v155, v155, v158
	v_add_f32_e32 v154, v154, v155
	ds_bpermute_b32 v155, v172, v154
	s_waitcnt lgkmcnt(0)
	v_add_f32_e32 v154, v154, v155
	v_mov_b32_e32 v155, v154
	s_nop 1
	v_permlane32_swap_b32_e32 v154, v155
	s_and_saveexec_b64 s[54:55], s[42:43]
	v_add_f32_e32 v154, v154, v155
	ds_write_b32 v201, v154 offset:2048
	s_or_b64 exec, exec, s[54:55]
	v_mul_f32_e32 v154, v47, v47
	v_mul_f32_e32 v155, v49, v49
	v_fmac_f32_e32 v154, v46, v46
	v_fmac_f32_e32 v155, v48, v48
	v_add_f32_e32 v154, v154, v155
	v_mul_f32_e32 v155, v43, v43
	v_mul_f32_e32 v158, v45, v45
	v_fmac_f32_e32 v155, v42, v42
	v_fmac_f32_e32 v158, v44, v44
	v_add_f32_e32 v155, v155, v158
	v_add_f32_e32 v154, v154, v155
	v_mul_f32_e32 v155, v39, v39
	v_mul_f32_e32 v158, v41, v41
	v_fmac_f32_e32 v155, v38, v38
	v_fmac_f32_e32 v158, v40, v40
	v_add_f32_e32 v155, v155, v158
	v_add_f32_e32 v154, v154, v155
	v_mul_f32_e32 v155, v35, v35
	v_mul_f32_e32 v158, v37, v37
	v_fmac_f32_e32 v155, v34, v34
	v_fmac_f32_e32 v158, v36, v36
	v_add_f32_e32 v155, v155, v158
	v_add_f32_e32 v154, v154, v155
	ds_bpermute_b32 v155, v172, v154
	s_waitcnt lgkmcnt(0)
	v_add_f32_e32 v154, v154, v155
	v_mov_b32_e32 v155, v154
	s_nop 1
	v_permlane32_swap_b32_e32 v154, v155
	s_and_saveexec_b64 s[54:55], s[42:43]
	v_add_f32_e32 v154, v154, v155
	ds_write_b32 v201, v154 offset:2304
	s_or_b64 exec, exec, s[54:55]
	v_mul_f32_e32 v154, v31, v31
	v_mul_f32_e32 v155, v33, v33
	v_fmac_f32_e32 v154, v30, v30
	v_fmac_f32_e32 v155, v32, v32
	v_add_f32_e32 v154, v154, v155
	v_mul_f32_e32 v155, v27, v27
	v_mul_f32_e32 v158, v29, v29
	v_fmac_f32_e32 v155, v26, v26
	v_fmac_f32_e32 v158, v28, v28
	v_add_f32_e32 v155, v155, v158
	v_add_f32_e32 v154, v154, v155
	v_mul_f32_e32 v155, v23, v23
	v_mul_f32_e32 v158, v25, v25
	v_fmac_f32_e32 v155, v22, v22
	v_fmac_f32_e32 v158, v24, v24
	v_add_f32_e32 v155, v155, v158
	v_add_f32_e32 v154, v154, v155
	v_mul_f32_e32 v155, v19, v19
	v_mul_f32_e32 v158, v21, v21
	v_fmac_f32_e32 v155, v18, v18
	v_fmac_f32_e32 v158, v20, v20
	v_add_f32_e32 v155, v155, v158
	v_add_f32_e32 v154, v154, v155
	ds_bpermute_b32 v155, v172, v154
	s_waitcnt lgkmcnt(0)
	v_add_f32_e32 v154, v154, v155
	v_mov_b32_e32 v155, v154
	s_nop 1
	v_permlane32_swap_b32_e32 v154, v155
	s_and_saveexec_b64 s[54:55], s[42:43]
	v_add_f32_e32 v154, v154, v155
	ds_write_b32 v201, v154 offset:2560
	s_or_b64 exec, exec, s[54:55]
	v_mul_f32_e32 v154, v15, v15
	v_mul_f32_e32 v155, v17, v17
	v_fmac_f32_e32 v154, v14, v14
	v_fmac_f32_e32 v155, v16, v16
	v_add_f32_e32 v154, v154, v155
	v_mul_f32_e32 v155, v11, v11
	v_mul_f32_e32 v158, v13, v13
	v_fmac_f32_e32 v155, v10, v10
	v_fmac_f32_e32 v158, v12, v12
	v_add_f32_e32 v155, v155, v158
	v_add_f32_e32 v154, v154, v155
	v_mul_f32_e32 v155, v7, v7
	v_mul_f32_e32 v158, v9, v9
	v_fmac_f32_e32 v155, v6, v6
	v_fmac_f32_e32 v158, v8, v8
	v_add_f32_e32 v155, v155, v158
	v_add_f32_e32 v154, v154, v155
	v_mul_f32_e32 v155, v3, v3
	v_mul_f32_e32 v158, v5, v5
	v_fmac_f32_e32 v155, v2, v2
	v_fmac_f32_e32 v158, v4, v4
	v_add_f32_e32 v155, v155, v158
	v_add_f32_e32 v154, v154, v155
	ds_bpermute_b32 v155, v172, v154
	s_waitcnt lgkmcnt(0)
	v_add_f32_e32 v154, v154, v155
	v_mov_b32_e32 v155, v154
	s_nop 1
	v_permlane32_swap_b32_e32 v154, v155
	s_and_saveexec_b64 s[54:55], s[42:43]
	v_add_f32_e32 v154, v154, v155
	ds_write_b32 v201, v154 offset:2816
	s_or_b64 exec, exec, s[54:55]
	s_add_u32 s12, s92, s12
	s_addc_u32 s13, s94, s13
	v_lshl_add_u64 v[154:155], v[136:137], 2, s[12:13]
	s_waitcnt lgkmcnt(0)
	s_barrier
	s_and_saveexec_b64 s[12:13], s[44:45]
	s_cbranch_execz .LBB0_122
	ds_read_b128 v[202:205], v180
	s_ashr_i32 s79, s78, 31
	v_lshl_add_u64 v[160:161], s[78:79], 2, v[154:155]
	s_waitcnt lgkmcnt(0)
	v_mov_b32_e32 v158, v203
	v_mov_b32_e32 v159, v204
	v_mov_b32_e32 v203, v205
	v_pk_add_f32 v[158:159], v[158:159], v[202:203]
	s_nop 0
	v_pk_add_f32 v[158:159], v[158:159], v[158:159] op_sel:[0,1] op_sel_hi:[1,0]
	global_store_dword v[160:161], v158, off sc1

;     __device__ __forceinline__ void exchange(const f32x4 (&acc)[2][2][4][2], const Unit& u, int e, int wr, int wc, int fr, int fq) const {
;     ...
;         if (tid < 256 && lid == 0) __hip_atomic_fetch_add(c, 1u, __ATOMIC_RELAXED, __HIP_MEMORY_SCOPE_AGENT);
;         if (wid == 0) { unsigned sp = 0;
;             while ((unsigned)__builtin_amdgcn_readfirstlane((int)__hip_atomic_load(c, __ATOMIC_RELAXED, __HIP_MEMORY_SCOPE_AGENT)) < 16u) { __builtin_amdgcn_s_sleep(2); if (++sp > (1u << 22)) break; }
;             __builtin_amdgcn_fence(__ATOMIC_ACQUIRE, "agent");
;             if (lid == 0) FL[0] = 1u; }
;     __device__ __forceinline__ void operator()(f32x4 (&acc)[2][2][4][2], const Unit& u, int wr, int wc, int fr, int fq) const {
;     ...
;             for (int m = 0; m < 4; ++m) { const int rl = ai * 128 + wr * 64 + m * 16 + fr; const float r1 = S[rl]; const size_t off = (size_t)(u.pm * 256 + rl) * DM + col0;
; #pragma unroll
;                 for (int bj = 0; bj < 2; ++bj) { const f32x4 xa = *(const f32x4*)(xin + off + bj * 128), xb = *(const f32x4*)(xin + off + bj * 128 + 4);
;                     const f32x4 ga = *(const f32x4*)(gpost + col0 + bj * 128), gb = *(const f32x4*)(gpost + col0 + bj * 128 + 4);
.LBB0_221:
	s_or_b64 exec, exec, s[50:51]
	s_lshl_b32 s68, s82, 8
	v_add_u32_e32 v250, s68, v169
	v_lshl_or_b32 v148, s76, 8, v189
	v_ashrrev_i32_e32 v251, 31, v250
	v_ashrrev_i32_e32 v149, 31, v148
	v_lshlrev_b64 v[250:251], 10, v[250:251]
	v_lshl_add_u64 v[250:251], v[250:251], 0, v[148:149]
	v_lshlrev_b64 v[162:163], 2, v[250:251]
	v_lshl_add_u64 v[164:165], s[34:35], 0, v[162:163]
	v_lshl_add_u64 v[154:155], v[148:149], 2, s[52:53]
	global_load_dwordx4 v[218:221], v[154:155], off
	global_load_dwordx4 v[222:225], v[154:155], off offset:16
	global_load_dwordx4 v[226:229], v[154:155], off offset:512
	global_load_dwordx4 v[230:233], v[154:155], off offset:528
	global_load_dwordx4 v[202:205], v[164:165], off offset:16
	global_load_dwordx4 v[206:209], v[164:165], off
	global_load_dwordx4 v[210:213], v[164:165], off offset:528
	global_load_dwordx4 v[214:217], v[164:165], off offset:512
	v_readlane_b32 s68, v253, 15
	v_readlane_b32 s69, v253, 16
	s_andn2_b64 vcc, exec, s[68:69]
	s_nop 0
	v_cndmask_b32_e64 v144, 0, 1, s[68:69]
	v_cmp_ne_u32_e64 s[50:51], 1, v144
	s_cbranch_vccnz .LBB0_233
	s_mov_b32 s68, 0x400001
	s_branch .LBB0_224

; #define LAS __attribute__((address_space(3)))
;     __device__ __forceinline__ void operator()(f32x4 (&acc)[2][2][4][2], const Unit& u, int wr, int wc, int fr, int fq) const {
;         const LAS float* S = (const LAS float*)(lds + EN_S);
;         const int col0 = u.pn * 256 + wc * 32 + 8 * fq;
;         exchange(acc, u, 0, wr, wc, fr, fq);
; #pragma unroll
;         for (int ai = 0; ai < 2; ++ai)
; #pragma unroll
;             for (int m = 0; m < 4; ++m) { const int rl = ai * 128 + wr * 64 + m * 16 + fr; const float r1 = S[rl]; const size_t off = (size_t)(u.pm * 256 + rl) * DM + col0;
; #pragma unroll
;                 for (int bj = 0; bj < 2; ++bj) { const f32x4 xa = *(const f32x4*)(xin + off + bj * 128), xb = *(const f32x4*)(xin + off + bj * 128 + 4);
;                     const f32x4 ga = *(const f32x4*)(gpost + col0 + bj * 128), gb = *(const f32x4*)(gpost + col0 + bj * 128 + 4);
;                     const f32x4 v0 = xa + acc[ai][bj][m][0] * r1 * ga, v1 = xb + acc[ai][bj][m][1] * r1 * gb;
;                     *(f32x4*)(xout + off + bj * 128) = v0; *(f32x4*)(xout + off + bj * 128 + 4) = v1; acc[ai][bj][m][0] = v0; acc[ai][bj][m][1] = v1; }
;                 asm volatile("" ::: "memory"); }
.LBB0_235:
	s_or_b64 exec, exec, s[84:85]
	s_lshl_b32 s54, s82, 8
	v_add_u32_e32 v144, s54, v169
	v_lshl_or_b32 v142, s76, 8, v189
	v_ashrrev_i32_e32 v145, 31, v144
	v_ashrrev_i32_e32 v143, 31, v142
	v_lshlrev_b64 v[146:147], 10, v[144:145]
	v_lshl_add_u64 v[146:147], v[146:147], 0, v[142:143]
	v_lshlrev_b64 v[162:163], 2, v[146:147]
	v_lshl_add_u64 v[164:165], s[34:35], 0, v[162:163]
	v_lshl_add_u64 v[154:155], v[142:143], 2, s[52:53]
	s_waitcnt lgkmcnt(0)
	s_barrier
	s_andn2_b64 vcc, exec, s[70:71]
	ds_read_b32 v154, v181
	v_lshl_add_u64 v[162:163], s[14:15], 0, v[162:163]
	v_add_u32_e32 v250, s54, v172
	v_ashrrev_i32_e32 v251, 31, v250
	v_lshlrev_b64 v[250:251], 10, v[250:251]
	v_lshl_add_u64 v[250:251], v[250:251], 0, v[142:143]
	v_lshlrev_b64 v[250:251], 2, v[250:251]
	v_lshl_add_u64 v[158:159], s[34:35], 0, v[250:251]
	v_lshl_add_u64 v[160:161], s[14:15], 0, v[250:251]
	ds_read_b32 v156, v182
	global_load_dwordx4 v[234:237], v[158:159], off offset:16
	global_load_dwordx4 v[238:241], v[158:159], off
	global_load_dwordx4 v[242:245], v[158:159], off offset:528
	global_load_dwordx4 v[246:249], v[158:159], off offset:512
	s_waitcnt lgkmcnt(1)
	v_pk_mul_f32 v[42:43], v[42:43], v[154:155] op_sel_hi:[1,0]
	v_pk_mul_f32 v[44:45], v[44:45], v[154:155] op_sel_hi:[1,0]
	v_pk_mul_f32 v[46:47], v[46:47], v[154:155] op_sel_hi:[1,0]
	v_pk_mul_f32 v[48:49], v[48:49], v[154:155] op_sel_hi:[1,0]
	v_pk_mul_f32 v[62:63], v[62:63], v[154:155] op_sel_hi:[1,0]
	v_pk_mul_f32 v[64:65], v[64:65], v[154:155] op_sel_hi:[1,0]
	v_pk_mul_f32 v[58:59], v[58:59], v[154:155] op_sel_hi:[1,0]
	v_pk_mul_f32 v[60:61], v[60:61], v[154:155] op_sel_hi:[1,0]
	s_waitcnt vmcnt(4)
	v_pk_fma_f32 v[46:47], v[46:47], v[222:223], v[202:203]
	v_pk_fma_f32 v[48:49], v[48:49], v[224:225], v[204:205]
	v_pk_fma_f32 v[42:43], v[42:43], v[218:219], v[206:207]
	v_pk_fma_f32 v[44:45], v[44:45], v[220:221], v[208:209]
	v_pk_fma_f32 v[58:59], v[58:59], v[230:231], v[210:211]
	v_pk_fma_f32 v[60:61], v[60:61], v[232:233], v[212:213]
	v_pk_fma_f32 v[62:63], v[62:63], v[226:227], v[214:215]
	v_pk_fma_f32 v[64:65], v[64:65], v[228:229], v[216:217]
	global_store_dwordx4 v[162:163], v[42:45], off
	global_store_dwordx4 v[162:163], v[46:49], off offset:16
	global_store_dwordx4 v[162:163], v[62:65], off offset:512
	global_store_dwordx4 v[162:163], v[58:61], off offset:528
	v_add_u32_e32 v250, s54, v173
	v_ashrrev_i32_e32 v251, 31, v250
	v_lshlrev_b64 v[250:251], 10, v[250:251]
	v_lshl_add_u64 v[250:251], v[250:251], 0, v[142:143]
	v_lshlrev_b64 v[250:251], 2, v[250:251]
	v_lshl_add_u64 v[164:165], s[34:35], 0, v[250:251]
	v_lshl_add_u64 v[162:163], s[14:15], 0, v[250:251]
	ds_read_b32 v154, v183
	global_load_dwordx4 v[202:205], v[164:165], off offset:16
	global_load_dwordx4 v[206:209], v[164:165], off
	global_load_dwordx4 v[210:213], v[164:165], off offset:528
	global_load_dwordx4 v[214:217], v[164:165], off offset:512
	s_waitcnt lgkmcnt(1)
	v_pk_mul_f32 v[66:67], v[66:67], v[156:157] op_sel_hi:[1,0]
	v_pk_mul_f32 v[68:69], v[68:69], v[156:157] op_sel_hi:[1,0]
	v_pk_mul_f32 v[70:71], v[70:71], v[156:157] op_sel_hi:[1,0]
	v_pk_mul_f32 v[72:73], v[72:73], v[156:157] op_sel_hi:[1,0]
	v_pk_mul_f32 v[86:87], v[86:87], v[156:157] op_sel_hi:[1,0]
	v_pk_mul_f32 v[88:89], v[88:89], v[156:157] op_sel_hi:[1,0]
	v_pk_mul_f32 v[82:83], v[82:83], v[156:157] op_sel_hi:[1,0]
	v_pk_mul_f32 v[84:85], v[84:85], v[156:157] op_sel_hi:[1,0]
	s_waitcnt vmcnt(8)
	v_pk_fma_f32 v[70:71], v[70:71], v[222:223], v[234:235]
	v_pk_fma_f32 v[72:73], v[72:73], v[224:225], v[236:237]
	v_pk_fma_f32 v[66:67], v[66:67], v[218:219], v[238:239]
	v_pk_fma_f32 v[68:69], v[68:69], v[220:221], v[240:241]
	v_pk_fma_f32 v[82:83], v[82:83], v[230:231], v[242:243]
	v_pk_fma_f32 v[84:85], v[84:85], v[232:233], v[244:245]
	v_pk_fma_f32 v[86:87], v[86:87], v[226:227], v[246:247]
	v_pk_fma_f32 v[88:89], v[88:89], v[228:229], v[248:249]
	global_store_dwordx4 v[160:161], v[66:69], off
	global_store_dwordx4 v[160:161], v[70:73], off offset:16
	global_store_dwordx4 v[160:161], v[86:89], off offset:512
	global_store_dwordx4 v[160:161], v[82:85], off offset:528
	v_add_u32_e32 v250, s54, v174
	v_ashrrev_i32_e32 v251, 31, v250
	v_lshlrev_b64 v[250:251], 10, v[250:251]
	v_lshl_add_u64 v[250:251], v[250:251], 0, v[142:143]
	v_lshlrev_b64 v[250:251], 2, v[250:251]
	v_lshl_add_u64 v[158:159], s[34:35], 0, v[250:251]
	v_lshl_add_u64 v[160:161], s[14:15], 0, v[250:251]
	ds_read_b32 v156, v184
	global_load_dwordx4 v[234:237], v[158:159], off offset:16
	global_load_dwordx4 v[238:241], v[158:159], off
	global_load_dwordx4 v[242:245], v[158:159], off offset:528
	global_load_dwordx4 v[246:249], v[158:159], off offset:512
	s_waitcnt lgkmcnt(1)
	v_pk_mul_f32 v[98:99], v[98:99], v[154:155] op_sel_hi:[1,0]
	v_pk_mul_f32 v[100:101], v[100:101], v[154:155] op_sel_hi:[1,0]
	v_pk_mul_f32 v[102:103], v[102:103], v[154:155] op_sel_hi:[1,0]
	v_pk_mul_f32 v[104:105], v[104:105], v[154:155] op_sel_hi:[1,0]
	v_pk_mul_f32 v[110:111], v[110:111], v[154:155] op_sel_hi:[1,0]
	v_pk_mul_f32 v[112:113], v[112:113], v[154:155] op_sel_hi:[1,0]
	v_pk_mul_f32 v[106:107], v[106:107], v[154:155] op_sel_hi:[1,0]
	v_pk_mul_f32 v[108:109], v[108:109], v[154:155] op_sel_hi:[1,0]
	s_waitcnt vmcnt(8)
;     __device__ __forceinline__ void operator()(f32x4 (&acc)[2][2][4][2], const Unit& u, int wr, int wc, int fr, int fq) const {
;     ...
;             for (int m = 0; m < 4; ++m) { const int rl = ai * 128 + wr * 64 + m * 16 + fr; const float r1 = S[rl]; const size_t off = (size_t)(u.pm * 256 + rl) * DM + col0;
; #pragma unroll
;                 for (int bj = 0; bj < 2; ++bj) { const f32x4 xa = *(const f32x4*)(xin + off + bj * 128), xb = *(const f32x4*)(xin + off + bj * 128 + 4);
;                     const f32x4 ga = *(const f32x4*)(gpost + col0 + bj * 128), gb = *(const f32x4*)(gpost + col0 + bj * 128 + 4);
;                     const f32x4 v0 = xa + acc[ai][bj][m][0] * r1 * ga, v1 = xb + acc[ai][bj][m][1] * r1 * gb;
;                     *(f32x4*)(xout + off + bj * 128) = v0; *(f32x4*)(xout + off + bj * 128 + 4) = v1; acc[ai][bj][m][0] = v0; acc[ai][bj][m][1] = v1; }
;                 asm volatile("" ::: "memory"); }
	v_pk_fma_f32 v[102:103], v[102:103], v[222:223], v[202:203]
	v_pk_fma_f32 v[104:105], v[104:105], v[224:225], v[204:205]
	v_pk_fma_f32 v[98:99], v[98:99], v[218:219], v[206:207]
	v_pk_fma_f32 v[100:101], v[100:101], v[220:221], v[208:209]
	v_pk_fma_f32 v[106:107], v[106:107], v[230:231], v[210:211]
	v_pk_fma_f32 v[108:109], v[108:109], v[232:233], v[212:213]
	v_pk_fma_f32 v[110:111], v[110:111], v[226:227], v[214:215]
	v_pk_fma_f32 v[112:113], v[112:113], v[228:229], v[216:217]
	global_store_dwordx4 v[162:163], v[98:101], off
	global_store_dwordx4 v[162:163], v[102:105], off offset:16
	global_store_dwordx4 v[162:163], v[110:113], off offset:512
	global_store_dwordx4 v[162:163], v[106:109], off offset:528
	v_add_u32_e32 v250, s54, v175
	v_ashrrev_i32_e32 v251, 31, v250
	v_lshlrev_b64 v[250:251], 10, v[250:251]
	v_lshl_add_u64 v[250:251], v[250:251], 0, v[142:143]
	v_lshlrev_b64 v[250:251], 2, v[250:251]
	v_lshl_add_u64 v[164:165], s[34:35], 0, v[250:251]
	v_lshl_add_u64 v[162:163], s[14:15], 0, v[250:251]
	ds_read_b32 v154, v185
	global_load_dwordx4 v[202:205], v[164:165], off offset:16
	global_load_dwordx4 v[206:209], v[164:165], off
	global_load_dwordx4 v[210:213], v[164:165], off offset:528
	global_load_dwordx4 v[214:217], v[164:165], off offset:512
	s_waitcnt lgkmcnt(1)
	v_pk_mul_f32 v[122:123], v[122:123], v[156:157] op_sel_hi:[1,0]
	v_pk_mul_f32 v[124:125], v[124:125], v[156:157] op_sel_hi:[1,0]
	v_pk_mul_f32 v[126:127], v[126:127], v[156:157] op_sel_hi:[1,0]
	v_pk_mul_f32 v[128:129], v[128:129], v[156:157] op_sel_hi:[1,0]
	v_pk_mul_f32 v[118:119], v[118:119], v[156:157] op_sel_hi:[1,0]
	v_pk_mul_f32 v[120:121], v[120:121], v[156:157] op_sel_hi:[1,0]
	v_pk_mul_f32 v[114:115], v[114:115], v[156:157] op_sel_hi:[1,0]
	v_pk_mul_f32 v[116:117], v[116:117], v[156:157] op_sel_hi:[1,0]
	s_waitcnt vmcnt(8)
	v_pk_fma_f32 v[126:127], v[126:127], v[222:223], v[234:235]
	v_pk_fma_f32 v[128:129], v[128:129], v[224:225], v[236:237]
	v_pk_fma_f32 v[122:123], v[122:123], v[218:219], v[238:239]
	v_pk_fma_f32 v[124:125], v[124:125], v[220:221], v[240:241]
	v_pk_fma_f32 v[114:115], v[114:115], v[230:231], v[242:243]
	v_pk_fma_f32 v[116:117], v[116:117], v[232:233], v[244:245]
	v_pk_fma_f32 v[118:119], v[118:119], v[226:227], v[246:247]
	v_pk_fma_f32 v[120:121], v[120:121], v[228:229], v[248:249]
	global_store_dwordx4 v[160:161], v[122:125], off
	global_store_dwordx4 v[160:161], v[126:129], off offset:16
	global_store_dwordx4 v[160:161], v[118:121], off offset:512
	global_store_dwordx4 v[160:161], v[114:117], off offset:528
	v_add_u32_e32 v250, s54, v176
	v_ashrrev_i32_e32 v251, 31, v250
	v_lshlrev_b64 v[250:251], 10, v[250:251]
	v_lshl_add_u64 v[250:251], v[250:251], 0, v[142:143]
	v_lshlrev_b64 v[250:251], 2, v[250:251]
	v_lshl_add_u64 v[158:159], s[34:35], 0, v[250:251]
	v_lshl_add_u64 v[160:161], s[14:15], 0, v[250:251]
	ds_read_b32 v156, v186
	global_load_dwordx4 v[234:237], v[158:159], off offset:16
	global_load_dwordx4 v[238:241], v[158:159], off
	global_load_dwordx4 v[242:245], v[158:159], off offset:528
	global_load_dwordx4 v[246:249], v[158:159], off offset:512
	s_waitcnt lgkmcnt(1)
	v_pk_mul_f32 v[94:95], v[94:95], v[154:155] op_sel_hi:[1,0]
	v_pk_mul_f32 v[96:97], v[96:97], v[154:155] op_sel_hi:[1,0]
	v_pk_mul_f32 v[90:91], v[90:91], v[154:155] op_sel_hi:[1,0]
	v_pk_mul_f32 v[92:93], v[92:93], v[154:155] op_sel_hi:[1,0]
	v_pk_mul_f32 v[78:79], v[78:79], v[154:155] op_sel_hi:[1,0]
	v_pk_mul_f32 v[80:81], v[80:81], v[154:155] op_sel_hi:[1,0]
	v_pk_mul_f32 v[74:75], v[74:75], v[154:155] op_sel_hi:[1,0]
	v_pk_mul_f32 v[76:77], v[76:77], v[154:155] op_sel_hi:[1,0]
	s_waitcnt vmcnt(8)
	v_pk_fma_f32 v[90:91], v[90:91], v[222:223], v[202:203]
	v_pk_fma_f32 v[92:93], v[92:93], v[224:225], v[204:205]
	v_pk_fma_f32 v[94:95], v[94:95], v[218:219], v[206:207]
	v_pk_fma_f32 v[96:97], v[96:97], v[220:221], v[208:209]
	v_pk_fma_f32 v[74:75], v[74:75], v[230:231], v[210:211]
	v_pk_fma_f32 v[76:77], v[76:77], v[232:233], v[212:213]
	v_pk_fma_f32 v[78:79], v[78:79], v[226:227], v[214:215]
	v_pk_fma_f32 v[80:81], v[80:81], v[228:229], v[216:217]
	global_store_dwordx4 v[162:163], v[94:97], off
	global_store_dwordx4 v[162:163], v[90:93], off offset:16
	global_store_dwordx4 v[162:163], v[78:81], off offset:512
	global_store_dwordx4 v[162:163], v[74:77], off offset:528
	v_add_u32_e32 v250, s54, v177
	v_ashrrev_i32_e32 v251, 31, v250
	v_lshlrev_b64 v[250:251], 10, v[250:251]
	v_lshl_add_u64 v[250:251], v[250:251], 0, v[142:143]
	v_lshlrev_b64 v[250:251], 2, v[250:251]
	v_lshl_add_u64 v[164:165], s[34:35], 0, v[250:251]
	v_lshl_add_u64 v[162:163], s[14:15], 0, v[250:251]
	ds_read_b32 v154, v187
	global_load_dwordx4 v[202:205], v[164:165], off offset:16
	global_load_dwordx4 v[206:209], v[164:165], off
	global_load_dwordx4 v[210:213], v[164:165], off offset:528
	global_load_dwordx4 v[214:217], v[164:165], off offset:512
	s_waitcnt lgkmcnt(1)
	v_pk_mul_f32 v[54:55], v[54:55], v[156:157] op_sel_hi:[1,0]
	v_pk_mul_f32 v[56:57], v[56:57], v[156:157] op_sel_hi:[1,0]
	v_pk_mul_f32 v[50:51], v[50:51], v[156:157] op_sel_hi:[1,0]
	v_pk_mul_f32 v[52:53], v[52:53], v[156:157] op_sel_hi:[1,0]
	v_pk_mul_f32 v[38:39], v[38:39], v[156:157] op_sel_hi:[1,0]
	v_pk_mul_f32 v[40:41], v[40:41], v[156:157] op_sel_hi:[1,0]
	v_pk_mul_f32 v[34:35], v[34:35], v[156:157] op_sel_hi:[1,0]
	v_pk_mul_f32 v[36:37], v[36:37], v[156:157] op_sel_hi:[1,0]
	s_waitcnt vmcnt(8)
; __device__ __forceinline__ float swap_add(float v) { auto rr = __builtin_amdgcn_permlane32_swap(__float_as_uint(v), __float_as_uint(v), false, false); return __uint_as_float(rr[0]) + __uint_as_float(rr[1]); }
;     __device__ __forceinline__ void exchange(const f32x4 (&acc)[2][2][4][2], const Unit& u, int e, int wr, int wc, int fr, int fq) const {
;     ...
;         for (int ai = 0; ai < 2; ++ai)
; #pragma unroll
;             for (int m = 0; m < 4; ++m) { float q = 0.f;
; #pragma unroll
;                 for (int bj = 0; bj < 2; ++bj)
; #pragma unroll
;                     for (int n = 0; n < 2; ++n) { const f32x4 v = acc[ai][bj][m][n]; q += (v[0] * v[0] + v[1] * v[1]) + (v[2] * v[2] + v[3] * v[3]); }
;                 q += __int_as_float(__builtin_amdgcn_ds_bpermute((lid ^ 16) << 2, __float_as_int(q))); q = swap_add(q);
;                 if (fq == 0) P[(ai * 128 + wr * 64 + m * 16 + fr) * 4 + wc] = q; }
;     __device__ __forceinline__ void operator()(f32x4 (&acc)[2][2][4][2], const Unit& u, int wr, int wc, int fr, int fq) const {
;     ...
;             for (int m = 0; m < 4; ++m) { const int rl = ai * 128 + wr * 64 + m * 16 + fr; const float r1 = S[rl]; const size_t off = (size_t)(u.pm * 256 + rl) * DM + col0;
; #pragma unroll
;                 for (int bj = 0; bj < 2; ++bj) { const f32x4 xa = *(const f32x4*)(xin + off + bj * 128), xb = *(const f32x4*)(xin + off + bj * 128 + 4);
;                     const f32x4 ga = *(const f32x4*)(gpost + col0 + bj * 128), gb = *(const f32x4*)(gpost + col0 + bj * 128 + 4);
;                     const f32x4 v0 = xa + acc[ai][bj][m][0] * r1 * ga, v1 = xb + acc[ai][bj][m][1] * r1 * gb;
;                     *(f32x4*)(xout + off + bj * 128) = v0; *(f32x4*)(xout + off + bj * 128 + 4) = v1; acc[ai][bj][m][0] = v0; acc[ai][bj][m][1] = v1; }
;                 asm volatile("" ::: "memory"); }
	v_pk_fma_f32 v[50:51], v[50:51], v[222:223], v[234:235]
	v_pk_fma_f32 v[52:53], v[52:53], v[224:225], v[236:237]
	v_pk_fma_f32 v[54:55], v[54:55], v[218:219], v[238:239]
	v_pk_fma_f32 v[56:57], v[56:57], v[220:221], v[240:241]
	v_pk_fma_f32 v[34:35], v[34:35], v[230:231], v[242:243]
	v_pk_fma_f32 v[36:37], v[36:37], v[232:233], v[244:245]
	v_pk_fma_f32 v[38:39], v[38:39], v[226:227], v[246:247]
	v_pk_fma_f32 v[40:41], v[40:41], v[228:229], v[248:249]
	global_store_dwordx4 v[160:161], v[54:57], off
	global_store_dwordx4 v[160:161], v[50:53], off offset:16
	global_store_dwordx4 v[160:161], v[38:41], off offset:512
	global_store_dwordx4 v[160:161], v[34:37], off offset:528
	v_add_u32_e32 v250, s54, v178
	v_ashrrev_i32_e32 v251, 31, v250
	v_lshlrev_b64 v[250:251], 10, v[250:251]
	v_lshl_add_u64 v[250:251], v[250:251], 0, v[142:143]
	v_lshlrev_b64 v[250:251], 2, v[250:251]
	v_lshl_add_u64 v[158:159], s[34:35], 0, v[250:251]
	v_lshl_add_u64 v[160:161], s[14:15], 0, v[250:251]
	ds_read_b32 v156, v188
	global_load_dwordx4 v[234:237], v[158:159], off offset:16
	global_load_dwordx4 v[238:241], v[158:159], off
	global_load_dwordx4 v[242:245], v[158:159], off offset:528
	global_load_dwordx4 v[246:249], v[158:159], off offset:512
	s_waitcnt lgkmcnt(1)
	v_pk_mul_f32 v[30:31], v[30:31], v[154:155] op_sel_hi:[1,0]
	v_pk_mul_f32 v[32:33], v[32:33], v[154:155] op_sel_hi:[1,0]
	v_pk_mul_f32 v[26:27], v[26:27], v[154:155] op_sel_hi:[1,0]
	v_pk_mul_f32 v[28:29], v[28:29], v[154:155] op_sel_hi:[1,0]
	v_pk_mul_f32 v[22:23], v[22:23], v[154:155] op_sel_hi:[1,0]
	v_pk_mul_f32 v[24:25], v[24:25], v[154:155] op_sel_hi:[1,0]
	v_pk_mul_f32 v[18:19], v[18:19], v[154:155] op_sel_hi:[1,0]
	v_pk_mul_f32 v[20:21], v[20:21], v[154:155] op_sel_hi:[1,0]
	s_waitcnt vmcnt(8)
	v_pk_fma_f32 v[26:27], v[26:27], v[222:223], v[202:203]
	v_pk_fma_f32 v[28:29], v[28:29], v[224:225], v[204:205]
	v_pk_fma_f32 v[30:31], v[30:31], v[218:219], v[206:207]
	v_pk_fma_f32 v[32:33], v[32:33], v[220:221], v[208:209]
	v_pk_fma_f32 v[18:19], v[18:19], v[230:231], v[210:211]
	v_pk_fma_f32 v[20:21], v[20:21], v[232:233], v[212:213]
	v_pk_fma_f32 v[22:23], v[22:23], v[226:227], v[214:215]
	v_pk_fma_f32 v[24:25], v[24:25], v[228:229], v[216:217]
	global_store_dwordx4 v[162:163], v[30:33], off
	global_store_dwordx4 v[162:163], v[26:29], off offset:16
	global_store_dwordx4 v[162:163], v[22:25], off offset:512
	global_store_dwordx4 v[162:163], v[18:21], off offset:528
	s_waitcnt lgkmcnt(0)
	v_pk_mul_f32 v[14:15], v[14:15], v[156:157] op_sel_hi:[1,0]
	v_pk_mul_f32 v[16:17], v[16:17], v[156:157] op_sel_hi:[1,0]
	v_pk_mul_f32 v[10:11], v[10:11], v[156:157] op_sel_hi:[1,0]
	v_pk_mul_f32 v[12:13], v[12:13], v[156:157] op_sel_hi:[1,0]
	v_pk_mul_f32 v[6:7], v[6:7], v[156:157] op_sel_hi:[1,0]
	v_pk_mul_f32 v[8:9], v[8:9], v[156:157] op_sel_hi:[1,0]
	v_pk_mul_f32 v[2:3], v[2:3], v[156:157] op_sel_hi:[1,0]
	v_pk_mul_f32 v[4:5], v[4:5], v[156:157] op_sel_hi:[1,0]
	s_waitcnt vmcnt(4)
	v_pk_fma_f32 v[10:11], v[10:11], v[222:223], v[234:235]
	v_pk_fma_f32 v[12:13], v[12:13], v[224:225], v[236:237]
	v_pk_fma_f32 v[14:15], v[14:15], v[218:219], v[238:239]
	v_pk_fma_f32 v[16:17], v[16:17], v[220:221], v[240:241]
	v_pk_fma_f32 v[2:3], v[2:3], v[230:231], v[242:243]
	v_pk_fma_f32 v[4:5], v[4:5], v[232:233], v[244:245]
	v_pk_fma_f32 v[6:7], v[6:7], v[226:227], v[246:247]
	v_pk_fma_f32 v[8:9], v[8:9], v[228:229], v[248:249]
	global_store_dwordx4 v[160:161], v[14:17], off
	global_store_dwordx4 v[160:161], v[10:13], off offset:16
	global_store_dwordx4 v[160:161], v[6:9], off offset:512
	global_store_dwordx4 v[160:161], v[2:5], off offset:528
	v_add_u32_e32 v146, s54, v172
	v_ashrrev_i32_e32 v147, 31, v146
	v_add_u32_e32 v148, s54, v173
	v_ashrrev_i32_e32 v149, 31, v148
	v_add_u32_e32 v150, s54, v174
	v_ashrrev_i32_e32 v151, 31, v150
	v_add_u32_e32 v152, s54, v175
	v_ashrrev_i32_e32 v153, 31, v152
	v_add_u32_e32 v156, s54, v176
	v_ashrrev_i32_e32 v157, 31, v156
	v_add_u32_e32 v158, s54, v177
	v_ashrrev_i32_e32 v159, 31, v158
	v_add_u32_e32 v166, s54, v178
	v_ashrrev_i32_e32 v167, 31, v166
	s_cbranch_vccnz .LBB0_272
	v_mul_f32_e32 v154, v43, v43
	v_mul_f32_e32 v155, v45, v45
	v_fmac_f32_e32 v154, v42, v42
	v_fmac_f32_e32 v155, v44, v44
	v_add_f32_e32 v154, v154, v155
	v_mul_f32_e32 v155, v47, v47
	v_mul_f32_e32 v160, v49, v49
	v_fmac_f32_e32 v155, v46, v46
	v_fmac_f32_e32 v160, v48, v48
	v_add_f32_e32 v155, v155, v160
	v_add_f32_e32 v154, v154, v155
	v_mul_f32_e32 v155, v63, v63
	v_mul_f32_e32 v160, v65, v65
	v_fmac_f32_e32 v155, v62, v62
	v_fmac_f32_e32 v160, v64, v64
	v_add_f32_e32 v155, v155, v160
	v_add_f32_e32 v154, v154, v155
	v_mul_f32_e32 v155, v59, v59
	v_mul_f32_e32 v160, v61, v61
	v_fmac_f32_e32 v155, v58, v58
	v_fmac_f32_e32 v160, v60, v60
	v_add_f32_e32 v155, v155, v160
	v_add_f32_e32 v154, v154, v155
	ds_bpermute_b32 v155, v171, v154
	s_waitcnt lgkmcnt(0)
	v_add_f32_e32 v154, v154, v155
	v_mov_b32_e32 v155, v154
	s_nop 1
	v_permlane32_swap_b32_e32 v154, v155
	s_and_saveexec_b64 s[54:55], s[42:43]
	v_add_f32_e32 v154, v154, v155
	ds_write_b32 v191, v154
	s_or_b64 exec, exec, s[54:55]
	v_mul_f32_e32 v154, v67, v67
	v_mul_f32_e32 v155, v69, v69
	v_fmac_f32_e32 v154, v66, v66
	v_fmac_f32_e32 v155, v68, v68
	v_add_f32_e32 v154, v154, v155
	v_mul_f32_e32 v155, v71, v71
	v_mul_f32_e32 v160, v73, v73
	v_fmac_f32_e32 v155, v70, v70
	v_fmac_f32_e32 v160, v72, v72
	v_add_f32_e32 v155, v155, v160
	v_add_f32_e32 v154, v154, v155
	v_mul_f32_e32 v155, v87, v87
	v_mul_f32_e32 v160, v89, v89
	v_fmac_f32_e32 v155, v86, v86
	v_fmac_f32_e32 v160, v88, v88
	v_add_f32_e32 v155, v155, v160
	v_add_f32_e32 v154, v154, v155
	v_mul_f32_e32 v155, v83, v83
	v_mul_f32_e32 v160, v85, v85
	v_fmac_f32_e32 v155, v82, v82
	v_fmac_f32_e32 v160, v84, v84
	v_add_f32_e32 v155, v155, v160
	v_add_f32_e32 v154, v154, v155
	ds_bpermute_b32 v155, v171, v154
	s_waitcnt lgkmcnt(0)
; __device__ __forceinline__ float swap_add(float v) { auto rr = __builtin_amdgcn_permlane32_swap(__float_as_uint(v), __float_as_uint(v), false, false); return __uint_as_float(rr[0]) + __uint_as_float(rr[1]); }
;     __device__ __forceinline__ void exchange(const f32x4 (&acc)[2][2][4][2], const Unit& u, int e, int wr, int wc, int fr, int fq) const {
;     ...
;         for (int ai = 0; ai < 2; ++ai)
; #pragma unroll
;             for (int m = 0; m < 4; ++m) { float q = 0.f;
; #pragma unroll
;                 for (int bj = 0; bj < 2; ++bj)
; #pragma unroll
;                     for (int n = 0; n < 2; ++n) { const f32x4 v = acc[ai][bj][m][n]; q += (v[0] * v[0] + v[1] * v[1]) + (v[2] * v[2] + v[3] * v[3]); }
;                 q += __int_as_float(__builtin_amdgcn_ds_bpermute((lid ^ 16) << 2, __float_as_int(q))); q = swap_add(q);
;                 if (fq == 0) P[(ai * 128 + wr * 64 + m * 16 + fr) * 4 + wc] = q; }
;         __syncthreads();
;         float* xb = xbuf + (size_t)e * T * 4 + (size_t)u.pm * 256 * 4; unsigned* c = cnt + (e * 64 + u.pm) * 64;
;         if (tid < 256) { const float tot = (P[tid * 4] + P[tid * 4 + 1]) + (P[tid * 4 + 2] + P[tid * 4 + 3]);
;             __hip_atomic_store(xb + tid * 4 + u.pn, tot, __ATOMIC_RELAXED, __HIP_MEMORY_SCOPE_AGENT); }
	v_add_f32_e32 v154, v154, v155
	v_mov_b32_e32 v155, v154
	s_nop 1
	v_permlane32_swap_b32_e32 v154, v155
	s_and_saveexec_b64 s[54:55], s[42:43]
	v_add_f32_e32 v154, v154, v155
	ds_write_b32 v191, v154 offset:256
	s_or_b64 exec, exec, s[54:55]
	v_mul_f32_e32 v154, v99, v99
	v_mul_f32_e32 v155, v101, v101
	v_fmac_f32_e32 v154, v98, v98
	v_fmac_f32_e32 v155, v100, v100
	v_add_f32_e32 v154, v154, v155
	v_mul_f32_e32 v155, v103, v103
	v_mul_f32_e32 v160, v105, v105
	v_fmac_f32_e32 v155, v102, v102
	v_fmac_f32_e32 v160, v104, v104
	v_add_f32_e32 v155, v155, v160
	v_add_f32_e32 v154, v154, v155
	v_mul_f32_e32 v155, v111, v111
	v_mul_f32_e32 v160, v113, v113
	v_fmac_f32_e32 v155, v110, v110
	v_fmac_f32_e32 v160, v112, v112
	v_add_f32_e32 v155, v155, v160
	v_add_f32_e32 v154, v154, v155
	v_mul_f32_e32 v155, v107, v107
	v_mul_f32_e32 v160, v109, v109
	v_fmac_f32_e32 v155, v106, v106
	v_fmac_f32_e32 v160, v108, v108
	v_add_f32_e32 v155, v155, v160
	v_add_f32_e32 v154, v154, v155
	ds_bpermute_b32 v155, v171, v154
	s_waitcnt lgkmcnt(0)
	v_add_f32_e32 v154, v154, v155
	v_mov_b32_e32 v155, v154
	s_nop 1
	v_permlane32_swap_b32_e32 v154, v155
	s_and_saveexec_b64 s[54:55], s[42:43]
	v_add_f32_e32 v154, v154, v155
	ds_write_b32 v191, v154 offset:512
	s_or_b64 exec, exec, s[54:55]
	v_mul_f32_e32 v154, v123, v123
	v_mul_f32_e32 v155, v125, v125
	v_fmac_f32_e32 v154, v122, v122
	v_fmac_f32_e32 v155, v124, v124
	v_add_f32_e32 v154, v154, v155
	v_mul_f32_e32 v155, v127, v127
	v_mul_f32_e32 v160, v129, v129
	v_fmac_f32_e32 v155, v126, v126
	v_fmac_f32_e32 v160, v128, v128
	v_add_f32_e32 v155, v155, v160
	v_add_f32_e32 v154, v154, v155
	v_mul_f32_e32 v155, v119, v119
	v_mul_f32_e32 v160, v121, v121
	v_fmac_f32_e32 v155, v118, v118
	v_fmac_f32_e32 v160, v120, v120
	v_add_f32_e32 v155, v155, v160
	v_add_f32_e32 v154, v154, v155
	v_mul_f32_e32 v155, v115, v115
	v_mul_f32_e32 v160, v117, v117
	v_fmac_f32_e32 v155, v114, v114
	v_fmac_f32_e32 v160, v116, v116
	v_add_f32_e32 v155, v155, v160
	v_add_f32_e32 v154, v154, v155
	ds_bpermute_b32 v155, v171, v154
	s_waitcnt lgkmcnt(0)
	v_add_f32_e32 v154, v154, v155
	v_mov_b32_e32 v155, v154
	s_nop 1
	v_permlane32_swap_b32_e32 v154, v155
	s_and_saveexec_b64 s[54:55], s[42:43]
	v_add_f32_e32 v154, v154, v155
	ds_write_b32 v191, v154 offset:768
	s_or_b64 exec, exec, s[54:55]
	v_mul_f32_e32 v154, v95, v95
	v_mul_f32_e32 v155, v97, v97
	v_fmac_f32_e32 v154, v94, v94
	v_fmac_f32_e32 v155, v96, v96
	v_add_f32_e32 v154, v154, v155
	v_mul_f32_e32 v155, v91, v91
	v_mul_f32_e32 v160, v93, v93
	v_fmac_f32_e32 v155, v90, v90
	v_fmac_f32_e32 v160, v92, v92
	v_add_f32_e32 v155, v155, v160
	v_add_f32_e32 v154, v154, v155
	v_mul_f32_e32 v155, v79, v79
	v_mul_f32_e32 v160, v81, v81
	v_fmac_f32_e32 v155, v78, v78
	v_fmac_f32_e32 v160, v80, v80
	v_add_f32_e32 v155, v155, v160
	v_add_f32_e32 v154, v154, v155
	v_mul_f32_e32 v155, v75, v75
	v_mul_f32_e32 v160, v77, v77
	v_fmac_f32_e32 v155, v74, v74
	v_fmac_f32_e32 v160, v76, v76
	v_add_f32_e32 v155, v155, v160
	v_add_f32_e32 v154, v154, v155
	ds_bpermute_b32 v155, v171, v154
	s_waitcnt lgkmcnt(0)
	v_add_f32_e32 v154, v154, v155
	v_mov_b32_e32 v155, v154
	s_nop 1
	v_permlane32_swap_b32_e32 v154, v155
	s_and_saveexec_b64 s[54:55], s[42:43]
	v_add_f32_e32 v154, v154, v155
	ds_write_b32 v191, v154 offset:2048
	s_or_b64 exec, exec, s[54:55]
	v_mul_f32_e32 v154, v55, v55
	v_mul_f32_e32 v155, v57, v57
	v_fmac_f32_e32 v154, v54, v54
	v_fmac_f32_e32 v155, v56, v56
	v_add_f32_e32 v154, v154, v155
	v_mul_f32_e32 v155, v51, v51
	v_mul_f32_e32 v160, v53, v53
	v_fmac_f32_e32 v155, v50, v50
	v_fmac_f32_e32 v160, v52, v52
	v_add_f32_e32 v155, v155, v160
	v_add_f32_e32 v154, v154, v155
	v_mul_f32_e32 v155, v39, v39
	v_mul_f32_e32 v160, v41, v41
	v_fmac_f32_e32 v155, v38, v38
	v_fmac_f32_e32 v160, v40, v40
	v_add_f32_e32 v155, v155, v160
	v_add_f32_e32 v154, v154, v155
	v_mul_f32_e32 v155, v35, v35
	v_mul_f32_e32 v160, v37, v37
	v_fmac_f32_e32 v155, v34, v34
	v_fmac_f32_e32 v160, v36, v36
	v_add_f32_e32 v155, v155, v160
	v_add_f32_e32 v154, v154, v155
	ds_bpermute_b32 v155, v171, v154
	s_waitcnt lgkmcnt(0)
	v_add_f32_e32 v154, v154, v155
	v_mov_b32_e32 v155, v154
	s_nop 1
	v_permlane32_swap_b32_e32 v154, v155
	s_and_saveexec_b64 s[54:55], s[42:43]
	v_add_f32_e32 v154, v154, v155
	ds_write_b32 v191, v154 offset:2304
	s_or_b64 exec, exec, s[54:55]
	v_mul_f32_e32 v154, v31, v31
	v_mul_f32_e32 v155, v33, v33
	v_fmac_f32_e32 v154, v30, v30
	v_fmac_f32_e32 v155, v32, v32
	v_add_f32_e32 v154, v154, v155
	v_mul_f32_e32 v155, v27, v27
	v_mul_f32_e32 v160, v29, v29
	v_fmac_f32_e32 v155, v26, v26
	v_fmac_f32_e32 v160, v28, v28
	v_add_f32_e32 v155, v155, v160
	v_add_f32_e32 v154, v154, v155
	v_mul_f32_e32 v155, v23, v23
	v_mul_f32_e32 v160, v25, v25
	v_fmac_f32_e32 v155, v22, v22
	v_fmac_f32_e32 v160, v24, v24
	v_add_f32_e32 v155, v155, v160
	v_add_f32_e32 v154, v154, v155
	v_mul_f32_e32 v155, v19, v19
	v_mul_f32_e32 v160, v21, v21
	v_fmac_f32_e32 v155, v18, v18
	v_fmac_f32_e32 v160, v20, v20
	v_add_f32_e32 v155, v155, v160
	v_add_f32_e32 v154, v154, v155
	ds_bpermute_b32 v155, v171, v154
	s_waitcnt lgkmcnt(0)
	v_add_f32_e32 v154, v154, v155
	v_mov_b32_e32 v155, v154
	s_nop 1
	v_permlane32_swap_b32_e32 v154, v155
	s_and_saveexec_b64 s[54:55], s[42:43]
	v_add_f32_e32 v154, v154, v155
	ds_write_b32 v191, v154 offset:2560
	s_or_b64 exec, exec, s[54:55]
	v_mul_f32_e32 v154, v15, v15
	v_mul_f32_e32 v155, v17, v17
	v_fmac_f32_e32 v154, v14, v14
	v_fmac_f32_e32 v155, v16, v16
	v_add_f32_e32 v154, v154, v155
	v_mul_f32_e32 v155, v11, v11
	v_mul_f32_e32 v160, v13, v13
	v_fmac_f32_e32 v155, v10, v10
	v_fmac_f32_e32 v160, v12, v12
	v_add_f32_e32 v155, v155, v160
	v_add_f32_e32 v154, v154, v155
	v_mul_f32_e32 v155, v7, v7
	v_mul_f32_e32 v160, v9, v9
	v_fmac_f32_e32 v155, v6, v6
	v_fmac_f32_e32 v160, v8, v8
	v_add_f32_e32 v155, v155, v160
	v_add_f32_e32 v154, v154, v155
	v_mul_f32_e32 v155, v3, v3
	v_mul_f32_e32 v160, v5, v5
	v_fmac_f32_e32 v155, v2, v2
	v_fmac_f32_e32 v160, v4, v4
	v_add_f32_e32 v155, v155, v160
	v_add_f32_e32 v154, v154, v155
	ds_bpermute_b32 v155, v171, v154
	s_waitcnt lgkmcnt(0)
	v_add_f32_e32 v154, v154, v155
	v_mov_b32_e32 v155, v154
	s_nop 1
	v_permlane32_swap_b32_e32 v154, v155
	s_and_saveexec_b64 s[54:55], s[42:43]
	v_add_f32_e32 v154, v154, v155
	ds_write_b32 v191, v154 offset:2816
	s_or_b64 exec, exec, s[54:55]
	s_add_u32 s12, s97, s12
	s_addc_u32 s13, s72, s13
	v_lshl_add_u64 v[154:155], v[136:137], 2, s[12:13]
	s_waitcnt lgkmcnt(0)
	s_barrier
	s_and_saveexec_b64 s[12:13], s[44:45]
	s_cbranch_execz .LBB0_254
	ds_read_b128 v[202:205], v179
	s_ashr_i32 s77, s76, 31
	v_lshl_add_u64 v[162:163], s[76:77], 2, v[154:155]
	s_waitcnt lgkmcnt(0)
	v_mov_b32_e32 v160, v203
	v_mov_b32_e32 v161, v204
	v_mov_b32_e32 v203, v205
	v_pk_add_f32 v[160:161], v[160:161], v[202:203]
	s_nop 0
	v_pk_add_f32 v[160:161], v[160:161], v[160:161] op_sel:[0,1] op_sel_hi:[1,0]
	global_store_dword v[162:163], v160, off sc1
